# plus: modulation GEMV k-loop keeps 64 (was 16) w_mod loads in flight per thread
# speedup vs baseline: 1.0015x; 1.0015x over previous
; __device__ __forceinline__ void p0_job(const Params& p, char* smem, int job) {
;     ...
;     int cj = tid & 63, ks = tid >> 6, col = cch * 64 + cj;
;     const float* W = p.w_mod + (size_t)l * 1024 * 6144;
;     float a0 = 0.f, a1 = 0.f, a2 = 0.f;
;     for (int k = ks * 256; k < ks * 256 + 256; ++k) {
;       float w = W[(size_t)k * 6144 + col];
;       a0 += sv[k] * w; a1 += sv[1024 + k] * w; a2 += sv[2048 + k] * w;
;     }
.LBB0_89:
	v_lshl_add_u64 v[24:25], v[8:9], 0, s[0:1]
	global_load_dword v186, v[24:25], off
	v_add_co_u32_e32 v26, vcc, 0x6000, v24
	s_nop 1
	v_addc_co_u32_e32 v27, vcc, 0, v25, vcc
	global_load_dword v187, v[26:27], off
	v_add_co_u32_e32 v26, vcc, 0xc000, v24
	s_nop 1
	v_addc_co_u32_e32 v27, vcc, 0, v25, vcc
	global_load_dword v188, v[26:27], off
	v_add_co_u32_e32 v26, vcc, 0x12000, v24
	s_nop 1
	v_addc_co_u32_e32 v27, vcc, 0, v25, vcc
	global_load_dword v189, v[26:27], off
	v_add_co_u32_e32 v26, vcc, 0x18000, v24
	s_nop 1
	v_addc_co_u32_e32 v27, vcc, 0, v25, vcc
	global_load_dword v190, v[26:27], off
	v_add_co_u32_e32 v26, vcc, 0x1e000, v24
	s_nop 1
	v_addc_co_u32_e32 v27, vcc, 0, v25, vcc
	global_load_dword v191, v[26:27], off
	v_add_co_u32_e32 v26, vcc, 0x24000, v24
	s_nop 1
	v_addc_co_u32_e32 v27, vcc, 0, v25, vcc
	global_load_dword v192, v[26:27], off
	v_add_co_u32_e32 v26, vcc, 0x2a000, v24
	s_nop 1
	v_addc_co_u32_e32 v27, vcc, 0, v25, vcc
	global_load_dword v193, v[26:27], off
	v_add_co_u32_e32 v26, vcc, 0x30000, v24
	s_nop 1
	v_addc_co_u32_e32 v27, vcc, 0, v25, vcc
	global_load_dword v194, v[26:27], off
	v_add_co_u32_e32 v26, vcc, 0x36000, v24
	s_nop 1
	v_addc_co_u32_e32 v27, vcc, 0, v25, vcc
	global_load_dword v195, v[26:27], off
	v_add_co_u32_e32 v26, vcc, 0x3c000, v24
	s_nop 1
	v_addc_co_u32_e32 v27, vcc, 0, v25, vcc
	global_load_dword v196, v[26:27], off
	v_add_co_u32_e32 v26, vcc, 0x42000, v24
	s_nop 1
	v_addc_co_u32_e32 v27, vcc, 0, v25, vcc
	global_load_dword v197, v[26:27], off
	v_add_co_u32_e32 v26, vcc, 0x48000, v24
	s_nop 1
	v_addc_co_u32_e32 v27, vcc, 0, v25, vcc
	global_load_dword v198, v[26:27], off
	v_add_co_u32_e32 v26, vcc, 0x4e000, v24
	s_nop 1
	v_addc_co_u32_e32 v27, vcc, 0, v25, vcc
	global_load_dword v199, v[26:27], off
	v_add_co_u32_e32 v26, vcc, 0x54000, v24
	s_nop 1
	v_addc_co_u32_e32 v27, vcc, 0, v25, vcc
	global_load_dword v200, v[26:27], off
	v_add_co_u32_e32 v26, vcc, 0x5a000, v24
	s_nop 1
	v_addc_co_u32_e32 v27, vcc, 0, v25, vcc
	global_load_dword v201, v[26:27], off
	v_add_co_u32_e32 v26, vcc, 0x60000, v24
	s_nop 1
	v_addc_co_u32_e32 v27, vcc, 0, v25, vcc
	global_load_dword v202, v[26:27], off
	v_add_co_u32_e32 v26, vcc, 0x66000, v24
	s_nop 1
	v_addc_co_u32_e32 v27, vcc, 0, v25, vcc
	global_load_dword v203, v[26:27], off
	v_add_co_u32_e32 v26, vcc, 0x6c000, v24
	s_nop 1
	v_addc_co_u32_e32 v27, vcc, 0, v25, vcc
	global_load_dword v204, v[26:27], off
	v_add_co_u32_e32 v26, vcc, 0x72000, v24
	s_nop 1
	v_addc_co_u32_e32 v27, vcc, 0, v25, vcc
	global_load_dword v205, v[26:27], off
	v_add_co_u32_e32 v26, vcc, 0x78000, v24
	s_nop 1
	v_addc_co_u32_e32 v27, vcc, 0, v25, vcc
	global_load_dword v206, v[26:27], off
	v_add_co_u32_e32 v26, vcc, 0x7e000, v24
	s_nop 1
	v_addc_co_u32_e32 v27, vcc, 0, v25, vcc
	global_load_dword v207, v[26:27], off
	v_add_co_u32_e32 v26, vcc, 0x84000, v24
	s_nop 1
	v_addc_co_u32_e32 v27, vcc, 0, v25, vcc
	global_load_dword v208, v[26:27], off
	v_add_co_u32_e32 v26, vcc, 0x8a000, v24
	s_nop 1
	v_addc_co_u32_e32 v27, vcc, 0, v25, vcc
	global_load_dword v209, v[26:27], off
	v_add_co_u32_e32 v26, vcc, 0x90000, v24
	s_nop 1
	v_addc_co_u32_e32 v27, vcc, 0, v25, vcc
	global_load_dword v210, v[26:27], off
	v_add_co_u32_e32 v26, vcc, 0x96000, v24
	s_nop 1
	v_addc_co_u32_e32 v27, vcc, 0, v25, vcc
	global_load_dword v211, v[26:27], off
	v_add_co_u32_e32 v26, vcc, 0x9c000, v24
	s_nop 1
	v_addc_co_u32_e32 v27, vcc, 0, v25, vcc
	global_load_dword v212, v[26:27], off
	v_add_co_u32_e32 v26, vcc, 0xa2000, v24
	s_nop 1
	v_addc_co_u32_e32 v27, vcc, 0, v25, vcc
	global_load_dword v213, v[26:27], off
	v_add_co_u32_e32 v26, vcc, 0xa8000, v24
	s_nop 1
	v_addc_co_u32_e32 v27, vcc, 0, v25, vcc
	global_load_dword v214, v[26:27], off
	v_add_co_u32_e32 v26, vcc, 0xae000, v24
	s_nop 1
	v_addc_co_u32_e32 v27, vcc, 0, v25, vcc
	global_load_dword v215, v[26:27], off
	v_add_co_u32_e32 v26, vcc, 0xb4000, v24
	s_nop 1
	v_addc_co_u32_e32 v27, vcc, 0, v25, vcc
	global_load_dword v216, v[26:27], off
	v_add_co_u32_e32 v26, vcc, 0xba000, v24
	s_nop 1
	v_addc_co_u32_e32 v27, vcc, 0, v25, vcc
	global_load_dword v217, v[26:27], off
	v_add_co_u32_e32 v26, vcc, 0xc0000, v24
	s_nop 1
	v_addc_co_u32_e32 v27, vcc, 0, v25, vcc
	global_load_dword v218, v[26:27], off
	v_add_co_u32_e32 v26, vcc, 0xc6000, v24
	s_nop 1
	v_addc_co_u32_e32 v27, vcc, 0, v25, vcc
	global_load_dword v219, v[26:27], off
	v_add_co_u32_e32 v26, vcc, 0xcc000, v24
	s_nop 1
	v_addc_co_u32_e32 v27, vcc, 0, v25, vcc
	global_load_dword v220, v[26:27], off
	v_add_co_u32_e32 v26, vcc, 0xd2000, v24
	s_nop 1
	v_addc_co_u32_e32 v27, vcc, 0, v25, vcc
	global_load_dword v221, v[26:27], off
	v_add_co_u32_e32 v26, vcc, 0xd8000, v24
	s_nop 1
	v_addc_co_u32_e32 v27, vcc, 0, v25, vcc
	global_load_dword v222, v[26:27], off
	v_add_co_u32_e32 v26, vcc, 0xde000, v24
	s_nop 1
	v_addc_co_u32_e32 v27, vcc, 0, v25, vcc
	global_load_dword v223, v[26:27], off
	v_add_co_u32_e32 v26, vcc, 0xe4000, v24
	s_nop 1
	v_addc_co_u32_e32 v27, vcc, 0, v25, vcc
	global_load_dword v224, v[26:27], off
	v_add_co_u32_e32 v26, vcc, 0xea000, v24
	s_nop 1
	v_addc_co_u32_e32 v27, vcc, 0, v25, vcc
	global_load_dword v225, v[26:27], off
	v_add_co_u32_e32 v26, vcc, 0xf0000, v24
	s_nop 1
	v_addc_co_u32_e32 v27, vcc, 0, v25, vcc
	global_load_dword v226, v[26:27], off
	v_add_co_u32_e32 v26, vcc, 0xf6000, v24
	s_nop 1
	v_addc_co_u32_e32 v27, vcc, 0, v25, vcc
	global_load_dword v227, v[26:27], off
	v_add_co_u32_e32 v26, vcc, 0xfc000, v24
	s_nop 1
	v_addc_co_u32_e32 v27, vcc, 0, v25, vcc
	global_load_dword v228, v[26:27], off
	v_add_co_u32_e32 v26, vcc, 0x102000, v24
	s_nop 1
	v_addc_co_u32_e32 v27, vcc, 0, v25, vcc
; __device__ __forceinline__ void p0_job(const Params& p, char* smem, int job) {
;     ...
;     float a0 = 0.f, a1 = 0.f, a2 = 0.f;
;     for (int k = ks * 256; k < ks * 256 + 256; ++k) {
;       float w = W[(size_t)k * 6144 + col];
;       a0 += sv[k] * w; a1 += sv[1024 + k] * w; a2 += sv[2048 + k] * w;
;     }
	global_load_dword v229, v[26:27], off
	v_add_co_u32_e32 v26, vcc, 0x108000, v24
	s_nop 1
	v_addc_co_u32_e32 v27, vcc, 0, v25, vcc
	global_load_dword v230, v[26:27], off
	v_add_co_u32_e32 v26, vcc, 0x10e000, v24
	s_nop 1
	v_addc_co_u32_e32 v27, vcc, 0, v25, vcc
	global_load_dword v231, v[26:27], off
	v_add_co_u32_e32 v26, vcc, 0x114000, v24
	s_nop 1
	v_addc_co_u32_e32 v27, vcc, 0, v25, vcc
	global_load_dword v232, v[26:27], off
	v_add_co_u32_e32 v26, vcc, 0x11a000, v24
	s_nop 1
	v_addc_co_u32_e32 v27, vcc, 0, v25, vcc
	global_load_dword v233, v[26:27], off
	v_add_co_u32_e32 v26, vcc, 0x120000, v24
	s_nop 1
	v_addc_co_u32_e32 v27, vcc, 0, v25, vcc
	global_load_dword v234, v[26:27], off
	v_add_co_u32_e32 v26, vcc, 0x126000, v24
	s_nop 1
	v_addc_co_u32_e32 v27, vcc, 0, v25, vcc
	global_load_dword v235, v[26:27], off
	v_add_co_u32_e32 v26, vcc, 0x12c000, v24
	s_nop 1
	v_addc_co_u32_e32 v27, vcc, 0, v25, vcc
	global_load_dword v240, v[26:27], off
	v_add_co_u32_e32 v26, vcc, 0x132000, v24
	s_nop 1
	v_addc_co_u32_e32 v27, vcc, 0, v25, vcc
	global_load_dword v241, v[26:27], off
	v_add_co_u32_e32 v26, vcc, 0x138000, v24
	s_nop 1
	v_addc_co_u32_e32 v27, vcc, 0, v25, vcc
	global_load_dword v242, v[26:27], off
	v_add_co_u32_e32 v26, vcc, 0x13e000, v24
	s_nop 1
	v_addc_co_u32_e32 v27, vcc, 0, v25, vcc
	global_load_dword v243, v[26:27], off
	v_add_co_u32_e32 v26, vcc, 0x144000, v24
	s_nop 1
	v_addc_co_u32_e32 v27, vcc, 0, v25, vcc
	global_load_dword v244, v[26:27], off
	v_add_co_u32_e32 v26, vcc, 0x14a000, v24
	s_nop 1
	v_addc_co_u32_e32 v27, vcc, 0, v25, vcc
	global_load_dword v245, v[26:27], off
	v_add_co_u32_e32 v26, vcc, 0x150000, v24
	s_nop 1
	v_addc_co_u32_e32 v27, vcc, 0, v25, vcc
	global_load_dword v246, v[26:27], off
	v_add_co_u32_e32 v26, vcc, 0x156000, v24
	s_nop 1
	v_addc_co_u32_e32 v27, vcc, 0, v25, vcc
	global_load_dword v247, v[26:27], off
	v_add_co_u32_e32 v26, vcc, 0x15c000, v24
	s_nop 1
	v_addc_co_u32_e32 v27, vcc, 0, v25, vcc
	global_load_dword v248, v[26:27], off
	v_add_co_u32_e32 v26, vcc, 0x162000, v24
	s_nop 1
	v_addc_co_u32_e32 v27, vcc, 0, v25, vcc
	global_load_dword v249, v[26:27], off
	v_add_co_u32_e32 v26, vcc, 0x168000, v24
	s_nop 1
	v_addc_co_u32_e32 v27, vcc, 0, v25, vcc
	global_load_dword v250, v[26:27], off
	v_add_co_u32_e32 v26, vcc, 0x16e000, v24
	s_nop 1
	v_addc_co_u32_e32 v27, vcc, 0, v25, vcc
	global_load_dword v251, v[26:27], off
	v_add_co_u32_e32 v26, vcc, 0x174000, v24
	s_nop 1
	v_addc_co_u32_e32 v27, vcc, 0, v25, vcc
	global_load_dword v252, v[26:27], off
	v_add_co_u32_e32 v26, vcc, 0x17a000, v24
	s_nop 1
	v_addc_co_u32_e32 v27, vcc, 0, v25, vcc
	global_load_dword v253, v[26:27], off
	s_add_u32 s0, s0, 0x180000
	s_addc_u32 s1, s1, 0
	s_waitcnt vmcnt(0)
	ds_read_b128 v[12:15], v7
	ds_read_b128 v[16:19], v7 offset:4096
	ds_read_b128 v[20:23], v7 offset:8192
	v_add_u32_e32 v7, 16, v7
	s_waitcnt lgkmcnt(0)
	v_fmac_f32_e32 v10, v186, v12
	v_fmac_f32_e32 v11, v186, v16
	v_fmac_f32_e32 v1, v186, v20
	v_fmac_f32_e32 v10, v187, v13
	v_fmac_f32_e32 v11, v187, v17
	v_fmac_f32_e32 v1, v187, v21
	v_fmac_f32_e32 v10, v188, v14
	v_fmac_f32_e32 v11, v188, v18
	v_fmac_f32_e32 v1, v188, v22
	v_fmac_f32_e32 v10, v189, v15
	v_fmac_f32_e32 v11, v189, v19
	v_fmac_f32_e32 v1, v189, v23
	ds_read_b128 v[12:15], v7
	ds_read_b128 v[16:19], v7 offset:4096
	ds_read_b128 v[20:23], v7 offset:8192
	v_add_u32_e32 v7, 16, v7
	s_waitcnt lgkmcnt(0)
	v_fmac_f32_e32 v10, v190, v12
	v_fmac_f32_e32 v11, v190, v16
	v_fmac_f32_e32 v1, v190, v20
	v_fmac_f32_e32 v10, v191, v13
	v_fmac_f32_e32 v11, v191, v17
	v_fmac_f32_e32 v1, v191, v21
	v_fmac_f32_e32 v10, v192, v14
	v_fmac_f32_e32 v11, v192, v18
	v_fmac_f32_e32 v1, v192, v22
	v_fmac_f32_e32 v10, v193, v15
	v_fmac_f32_e32 v11, v193, v19
	v_fmac_f32_e32 v1, v193, v23
	ds_read_b128 v[12:15], v7
	ds_read_b128 v[16:19], v7 offset:4096
	ds_read_b128 v[20:23], v7 offset:8192
	v_add_u32_e32 v7, 16, v7
	s_waitcnt lgkmcnt(0)
	v_fmac_f32_e32 v10, v194, v12
	v_fmac_f32_e32 v11, v194, v16
	v_fmac_f32_e32 v1, v194, v20
	v_fmac_f32_e32 v10, v195, v13
	v_fmac_f32_e32 v11, v195, v17
	v_fmac_f32_e32 v1, v195, v21
	v_fmac_f32_e32 v10, v196, v14
	v_fmac_f32_e32 v11, v196, v18
	v_fmac_f32_e32 v1, v196, v22
	v_fmac_f32_e32 v10, v197, v15
	v_fmac_f32_e32 v11, v197, v19
	v_fmac_f32_e32 v1, v197, v23
	ds_read_b128 v[12:15], v7
	ds_read_b128 v[16:19], v7 offset:4096
	ds_read_b128 v[20:23], v7 offset:8192
	v_add_u32_e32 v7, 16, v7
	s_waitcnt lgkmcnt(0)
	v_fmac_f32_e32 v10, v198, v12
	v_fmac_f32_e32 v11, v198, v16
	v_fmac_f32_e32 v1, v198, v20
	v_fmac_f32_e32 v10, v199, v13
	v_fmac_f32_e32 v11, v199, v17
	v_fmac_f32_e32 v1, v199, v21
	v_fmac_f32_e32 v10, v200, v14
	v_fmac_f32_e32 v11, v200, v18
	v_fmac_f32_e32 v1, v200, v22
	v_fmac_f32_e32 v10, v201, v15
	v_fmac_f32_e32 v11, v201, v19
	v_fmac_f32_e32 v1, v201, v23
	ds_read_b128 v[12:15], v7
	ds_read_b128 v[16:19], v7 offset:4096
	ds_read_b128 v[20:23], v7 offset:8192
	v_add_u32_e32 v7, 16, v7
	s_waitcnt lgkmcnt(0)
	v_fmac_f32_e32 v10, v202, v12
	v_fmac_f32_e32 v11, v202, v16
	v_fmac_f32_e32 v1, v202, v20
	v_fmac_f32_e32 v10, v203, v13
	v_fmac_f32_e32 v11, v203, v17
	v_fmac_f32_e32 v1, v203, v21
	v_fmac_f32_e32 v10, v204, v14
	v_fmac_f32_e32 v11, v204, v18
	v_fmac_f32_e32 v1, v204, v22
	v_fmac_f32_e32 v10, v205, v15
	v_fmac_f32_e32 v11, v205, v19
	v_fmac_f32_e32 v1, v205, v23
	ds_read_b128 v[12:15], v7
	ds_read_b128 v[16:19], v7 offset:4096
	ds_read_b128 v[20:23], v7 offset:8192
	v_add_u32_e32 v7, 16, v7
	s_waitcnt lgkmcnt(0)
; __device__ __forceinline__ void p0_job(const Params& p, char* smem, int job) {
;     ...
;     for (int k = ks * 256; k < ks * 256 + 256; ++k) {
;       float w = W[(size_t)k * 6144 + col];
;       a0 += sv[k] * w; a1 += sv[1024 + k] * w; a2 += sv[2048 + k] * w;
;     }
	v_fmac_f32_e32 v10, v206, v12
	v_fmac_f32_e32 v11, v206, v16
	v_fmac_f32_e32 v1, v206, v20
	v_fmac_f32_e32 v10, v207, v13
	v_fmac_f32_e32 v11, v207, v17
	v_fmac_f32_e32 v1, v207, v21
	v_fmac_f32_e32 v10, v208, v14
	v_fmac_f32_e32 v11, v208, v18
	v_fmac_f32_e32 v1, v208, v22
	v_fmac_f32_e32 v10, v209, v15
	v_fmac_f32_e32 v11, v209, v19
	v_fmac_f32_e32 v1, v209, v23
	ds_read_b128 v[12:15], v7
	ds_read_b128 v[16:19], v7 offset:4096
	ds_read_b128 v[20:23], v7 offset:8192
	v_add_u32_e32 v7, 16, v7
	s_waitcnt lgkmcnt(0)
	v_fmac_f32_e32 v10, v210, v12
	v_fmac_f32_e32 v11, v210, v16
	v_fmac_f32_e32 v1, v210, v20
	v_fmac_f32_e32 v10, v211, v13
	v_fmac_f32_e32 v11, v211, v17
	v_fmac_f32_e32 v1, v211, v21
	v_fmac_f32_e32 v10, v212, v14
	v_fmac_f32_e32 v11, v212, v18
	v_fmac_f32_e32 v1, v212, v22
	v_fmac_f32_e32 v10, v213, v15
	v_fmac_f32_e32 v11, v213, v19
	v_fmac_f32_e32 v1, v213, v23
	ds_read_b128 v[12:15], v7
	ds_read_b128 v[16:19], v7 offset:4096
	ds_read_b128 v[20:23], v7 offset:8192
	v_add_u32_e32 v7, 16, v7
	s_waitcnt lgkmcnt(0)
	v_fmac_f32_e32 v10, v214, v12
	v_fmac_f32_e32 v11, v214, v16
	v_fmac_f32_e32 v1, v214, v20
	v_fmac_f32_e32 v10, v215, v13
	v_fmac_f32_e32 v11, v215, v17
	v_fmac_f32_e32 v1, v215, v21
	v_fmac_f32_e32 v10, v216, v14
	v_fmac_f32_e32 v11, v216, v18
	v_fmac_f32_e32 v1, v216, v22
	v_fmac_f32_e32 v10, v217, v15
	v_fmac_f32_e32 v11, v217, v19
	v_fmac_f32_e32 v1, v217, v23
	ds_read_b128 v[12:15], v7
	ds_read_b128 v[16:19], v7 offset:4096
	ds_read_b128 v[20:23], v7 offset:8192
	v_add_u32_e32 v7, 16, v7
	s_waitcnt lgkmcnt(0)
	v_fmac_f32_e32 v10, v218, v12
	v_fmac_f32_e32 v11, v218, v16
	v_fmac_f32_e32 v1, v218, v20
	v_fmac_f32_e32 v10, v219, v13
	v_fmac_f32_e32 v11, v219, v17
	v_fmac_f32_e32 v1, v219, v21
	v_fmac_f32_e32 v10, v220, v14
	v_fmac_f32_e32 v11, v220, v18
	v_fmac_f32_e32 v1, v220, v22
	v_fmac_f32_e32 v10, v221, v15
	v_fmac_f32_e32 v11, v221, v19
	v_fmac_f32_e32 v1, v221, v23
	ds_read_b128 v[12:15], v7
	ds_read_b128 v[16:19], v7 offset:4096
	ds_read_b128 v[20:23], v7 offset:8192
	v_add_u32_e32 v7, 16, v7
	s_waitcnt lgkmcnt(0)
	v_fmac_f32_e32 v10, v222, v12
	v_fmac_f32_e32 v11, v222, v16
	v_fmac_f32_e32 v1, v222, v20
	v_fmac_f32_e32 v10, v223, v13
	v_fmac_f32_e32 v11, v223, v17
	v_fmac_f32_e32 v1, v223, v21
	v_fmac_f32_e32 v10, v224, v14
	v_fmac_f32_e32 v11, v224, v18
	v_fmac_f32_e32 v1, v224, v22
	v_fmac_f32_e32 v10, v225, v15
	v_fmac_f32_e32 v11, v225, v19
	v_fmac_f32_e32 v1, v225, v23
	ds_read_b128 v[12:15], v7
	ds_read_b128 v[16:19], v7 offset:4096
	ds_read_b128 v[20:23], v7 offset:8192
	v_add_u32_e32 v7, 16, v7
	s_waitcnt lgkmcnt(0)
	v_fmac_f32_e32 v10, v226, v12
	v_fmac_f32_e32 v11, v226, v16
	v_fmac_f32_e32 v1, v226, v20
	v_fmac_f32_e32 v10, v227, v13
	v_fmac_f32_e32 v11, v227, v17
	v_fmac_f32_e32 v1, v227, v21
	v_fmac_f32_e32 v10, v228, v14
	v_fmac_f32_e32 v11, v228, v18
	v_fmac_f32_e32 v1, v228, v22
	v_fmac_f32_e32 v10, v229, v15
	v_fmac_f32_e32 v11, v229, v19
	v_fmac_f32_e32 v1, v229, v23
	ds_read_b128 v[12:15], v7
	ds_read_b128 v[16:19], v7 offset:4096
	ds_read_b128 v[20:23], v7 offset:8192
	v_add_u32_e32 v7, 16, v7
	s_waitcnt lgkmcnt(0)
	v_fmac_f32_e32 v10, v230, v12
	v_fmac_f32_e32 v11, v230, v16
	v_fmac_f32_e32 v1, v230, v20
	v_fmac_f32_e32 v10, v231, v13
	v_fmac_f32_e32 v11, v231, v17
	v_fmac_f32_e32 v1, v231, v21
	v_fmac_f32_e32 v10, v232, v14
	v_fmac_f32_e32 v11, v232, v18
	v_fmac_f32_e32 v1, v232, v22
	v_fmac_f32_e32 v10, v233, v15
	v_fmac_f32_e32 v11, v233, v19
	v_fmac_f32_e32 v1, v233, v23
	ds_read_b128 v[12:15], v7
	ds_read_b128 v[16:19], v7 offset:4096
	ds_read_b128 v[20:23], v7 offset:8192
	v_add_u32_e32 v7, 16, v7
	s_waitcnt lgkmcnt(0)
	v_fmac_f32_e32 v10, v234, v12
	v_fmac_f32_e32 v11, v234, v16
	v_fmac_f32_e32 v1, v234, v20
	v_fmac_f32_e32 v10, v235, v13
	v_fmac_f32_e32 v11, v235, v17
	v_fmac_f32_e32 v1, v235, v21
	v_fmac_f32_e32 v10, v240, v14
	v_fmac_f32_e32 v11, v240, v18
	v_fmac_f32_e32 v1, v240, v22
	v_fmac_f32_e32 v10, v241, v15
	v_fmac_f32_e32 v11, v241, v19
	v_fmac_f32_e32 v1, v241, v23
	ds_read_b128 v[12:15], v7
	ds_read_b128 v[16:19], v7 offset:4096
	ds_read_b128 v[20:23], v7 offset:8192
	v_add_u32_e32 v7, 16, v7
	s_waitcnt lgkmcnt(0)
	v_fmac_f32_e32 v10, v242, v12
	v_fmac_f32_e32 v11, v242, v16
	v_fmac_f32_e32 v1, v242, v20
	v_fmac_f32_e32 v10, v243, v13
	v_fmac_f32_e32 v11, v243, v17
	v_fmac_f32_e32 v1, v243, v21
	v_fmac_f32_e32 v10, v244, v14
	v_fmac_f32_e32 v11, v244, v18
	v_fmac_f32_e32 v1, v244, v22
	v_fmac_f32_e32 v10, v245, v15
	v_fmac_f32_e32 v11, v245, v19
	v_fmac_f32_e32 v1, v245, v23
	ds_read_b128 v[12:15], v7
	ds_read_b128 v[16:19], v7 offset:4096
	ds_read_b128 v[20:23], v7 offset:8192
	v_add_u32_e32 v7, 16, v7
	s_waitcnt lgkmcnt(0)
	v_fmac_f32_e32 v10, v246, v12
	v_fmac_f32_e32 v11, v246, v16
	v_fmac_f32_e32 v1, v246, v20
	v_fmac_f32_e32 v10, v247, v13
	v_fmac_f32_e32 v11, v247, v17
	v_fmac_f32_e32 v1, v247, v21
	v_fmac_f32_e32 v10, v248, v14
	v_fmac_f32_e32 v11, v248, v18
	v_fmac_f32_e32 v1, v248, v22
	v_fmac_f32_e32 v10, v249, v15
	v_fmac_f32_e32 v11, v249, v19
	v_fmac_f32_e32 v1, v249, v23
	ds_read_b128 v[12:15], v7
	ds_read_b128 v[16:19], v7 offset:4096
	ds_read_b128 v[20:23], v7 offset:8192
	v_add_u32_e32 v7, 16, v7
	s_waitcnt lgkmcnt(0)
	v_fmac_f32_e32 v10, v250, v12
	v_fmac_f32_e32 v11, v250, v16
	v_fmac_f32_e32 v1, v250, v20
	v_fmac_f32_e32 v10, v251, v13
	v_fmac_f32_e32 v11, v251, v17
	v_fmac_f32_e32 v1, v251, v21
	v_fmac_f32_e32 v10, v252, v14
	v_fmac_f32_e32 v11, v252, v18
	v_fmac_f32_e32 v1, v252, v22
	v_fmac_f32_e32 v10, v253, v15
	v_fmac_f32_e32 v11, v253, v19
	v_fmac_f32_e32 v1, v253, v23
	s_cmp_eq_u32 s0, 0x600000
	s_cbranch_scc0 .LBB0_89
; __device__ __forceinline__ void p0_job(const Params& p, char* smem, int job) {
;     ...
;     __syncthreads();
;     sv[(ks * 3 + 0) * 64 + cj] = a0; sv[(ks * 3 + 1) * 64 + cj] = a1; sv[(ks * 3 + 2) * 64 + cj] = a2;
;     __syncthreads();
;     if (ks < 3) {
;       int v = ks;
;       float s = sv[(0 * 3 + v) * 64 + cj] + sv[(1 * 3 + v) * 64 + cj] + sv[(2 * 3 + v) * 64 + cj] + sv[(3 * 3 + v) * 64 + cj];
;       ((float*)(ws + OFF_MODS))[(l * 3 + v) * 6144 + col] = s + p.b_mod[l * 6144 + col];
;     }
	s_movk_i32 s0, 0x300
	v_mul_lo_u32 v7, v2, s0
	v_lshl_or_b32 v7, v4, 2, v7
	v_cmp_gt_i32_e32 vcc, 3, v2
	s_barrier
	ds_write2st64_b32 v7, v10, v11 offset1:1
	ds_write_b32 v7, v1 offset:512
	s_waitcnt lgkmcnt(0)
	s_barrier
	s_and_saveexec_b64 s[0:1], vcc
	s_cbranch_execz .LBB0_92
	s_mov_b32 s4, 0x3fffffc0
	ds_read_b32 v1, v3
	v_and_or_b32 v3, v6, s4, v4
	v_lshlrev_b32_e32 v3, 2, v3
	ds_read2st64_b32 v[6:7], v3 offset0:3 offset1:6
	ds_read_b32 v3, v3 offset:2304
	s_mul_i32 s4, s2, 0x1800
	v_readlane_b32 s68, v239, 7
	v_readlane_b32 s78, v239, 17
	s_waitcnt lgkmcnt(1)
	v_add_f32_e32 v1, v1, v6
	v_add_u32_e32 v6, s4, v0
	v_add_f32_e32 v1, v1, v7
	v_ashrrev_i32_e32 v7, 31, v6
	v_readlane_b32 s79, v239, 18
	s_waitcnt lgkmcnt(0)
	v_add_f32_e32 v1, v1, v3
	v_readlane_b32 s69, v239, 8
	v_lshl_add_u64 v[6:7], v[6:7], 2, s[78:79]
	global_load_dword v3, v[6:7], off
	v_readlane_b32 s70, v239, 9
	v_readlane_b32 s71, v239, 10
	v_readlane_b32 s72, v239, 11
	v_readlane_b32 s73, v239, 12
	v_readlane_b32 s74, v239, 13
	v_readlane_b32 s75, v239, 14
	v_readlane_b32 s76, v239, 15
	v_readlane_b32 s77, v239, 16
	v_readlane_b32 s80, v239, 19
	v_readlane_b32 s81, v239, 20
	v_readlane_b32 s82, v239, 21
	v_readlane_b32 s83, v239, 22
	s_waitcnt vmcnt(0)
	v_add_f32_e32 v4, v1, v3
	v_mad_u64_u32 v[2:3], s[4:5], s2, 3, v[2:3]
	s_movk_i32 s2, 0x1800
	v_mad_u64_u32 v[0:1], s[4:5], v2, s2, v[0:1]
	v_ashrrev_i32_e32 v1, 31, v0
	v_lshl_add_u64 v[0:1], v[0:1], 2, s[20:21]
	v_add_co_u32_e32 v0, vcc, 0x18e00000, v0
	s_nop 1
	v_addc_co_u32_e32 v1, vcc, 0, v1, vcc
	global_store_dword v[0:1], v4, off
